# diff-attention loop: the V tile's pad lanes (1 of every 9 sixteen-byte chunks) are masked out of the LDS-DMA via EXEC instead of loading duplicate data
# baseline (speedup 1.0000x reference)
; template <int MODE, bool FROZEN = false>
; __device__ __forceinline__ bool attn_unit(LAS unsigned char* lds, const Params& p, int l, int ua, int ub) {
;     ...
;         const float* lq = p.diff_lambda + (size_t)l * 256;
;         const float s1 = wave_sum(lq[lane] * lq[64 + lane]), s2 = wave_sum(lq[128 + lane] * lq[192 + lane]);
;         lam_init = 0.8f - 0.6f * expf(-0.3f * (float)l);
;         lam = expf(s1) - expf(s2) + lam_init;
;     ...
;     for (int i = 0; i < NKC; ++i) { const int cid = tid + 512 * i, row = cid / KCH, ch = cid % KCH; ksrc[i] = (unsigned)(row * NPROJ + kcol + ch * 8); kdst[i] = OFF_K + row * KPB + ch * 16; }
; #pragma unroll
;     for (int i = 0; i < NVC; ++i) { const int cid = tid + 512 * i, row = cid >> 3, ch = cid & 7; vsrc[i] = (unsigned)((vcol + row) * S + ch * 8); vdst[i] = OFF_V + row * VTP + (ch >> 1) * 32 + (ch & 1) * 8; }
.LBB0_116:
	v_mul_f32_e32 v55, 0x3fb8aa3b, v53
	s_mov_b32 s8, 0x3fb8aa3b
	v_fma_f32 v56, v53, s8, -v55
	v_fmac_f32_e32 v56, 0x32a5705f, v53
	v_rndne_f32_e32 v53, v55
	v_sub_f32_e32 v55, v55, v53
	v_add_f32_e32 v55, v55, v56
	v_mul_f32_e32 v56, 0x3fb8aa3b, v54
	v_fma_f32 v57, v54, s8, -v56
	v_fmac_f32_e32 v57, 0x32a5705f, v54
	v_rndne_f32_e32 v54, v56
	v_exp_f32_e32 v55, v55
	v_cvt_i32_f32_e32 v53, v53
	v_sub_f32_e32 v56, v56, v54
	v_add_f32_e32 v56, v56, v57
	v_exp_f32_e32 v56, v56
	v_cvt_i32_f32_e32 v54, v54
	v_ldexp_f32 v53, v55, v53
	v_cndmask_b32_e64 v53, 0, v53, s[40:41]
	v_mov_b32_e32 v55, 0x7f800000
	v_cndmask_b32_e64 v167, v55, v53, s[42:43]
	v_ldexp_f32 v53, v56, v54
	v_cndmask_b32_e64 v53, 0, v53, s[0:1]
	s_lshl_b32 s0, s51, 7
	s_and_b32 s0, s0, 0x2000
	s_lshl_b32 s1, s57, 7
	v_cndmask_b32_e64 v168, v55, v53, s[4:5]
	s_add_i32 s4, s0, s1
	s_or_b32 s4, s4, s58
	v_mul_u32_u24_e32 v53, 0x90, v52
	v_add_lshl_u32 v52, s4, v52, 2
	v_sub_u32_e32 v52, v32, v52
	s_or_b32 s1, s58, s1
	v_add3_u32 v101, 0, v53, v32
	v_add_u32_e32 v102, 0, v52
	s_add_i32 s1, s1, s0
	v_mov_b64_e32 v[98:99], v[50:51]
	v_mov_b64_e32 v[82:83], v[50:51]
	v_mov_b64_e32 v[66:67], v[50:51]
	s_add_i32 s8, s4, 0xffffff81
	s_sub_i32 s12, 33, s1
	s_mov_b32 s13, 0
	v_mov_b64_e32 v[96:97], v[48:49]
	v_mov_b64_e32 v[94:95], v[46:47]
	v_mov_b64_e32 v[92:93], v[44:45]
	v_mov_b64_e32 v[90:91], v[42:43]
	v_mov_b64_e32 v[88:89], v[40:41]
	v_mov_b64_e32 v[86:87], v[38:39]
	v_mov_b64_e32 v[84:85], v[36:37]
	v_mov_b64_e32 v[80:81], v[48:49]
	v_mov_b64_e32 v[78:79], v[46:47]
	v_mov_b64_e32 v[76:77], v[44:45]
	v_mov_b64_e32 v[74:75], v[42:43]
	v_mov_b64_e32 v[72:73], v[40:41]
	v_mov_b64_e32 v[70:71], v[38:39]
	v_mov_b64_e32 v[68:69], v[36:37]
	v_mov_b64_e32 v[64:65], v[48:49]
	v_mov_b64_e32 v[62:63], v[46:47]
	v_mov_b64_e32 v[60:61], v[44:45]
	v_mov_b64_e32 v[58:59], v[42:43]
	v_mov_b64_e32 v[56:57], v[40:41]
	v_mov_b64_e32 v[54:55], v[38:39]
	v_mov_b64_e32 v[52:53], v[36:37]
	v_mov_b64_e32 v[218:219], 0
	v_mov_b64_e32 v[220:221], 0
	v_mov_b64_e32 v[222:223], 0
	v_mov_b64_e32 v[224:225], 0
	v_mov_b64_e32 v[248:249], 0
	v_mov_b64_e32 v[250:251], 0
	v_mov_b64_e32 v[236:237], 0
	v_mov_b64_e32 v[238:239], 0
	v_mov_b64_e32 v[244:245], 0
	v_mov_b64_e32 v[246:247], 0
	s_waitcnt vmcnt(0)
	v_readfirstlane_b32 s98, v228
	s_lshr_b32 s98, s98, 6
	s_lshl_b32 s98, s98, 11
	v_lshrrev_b32_e32 v140, 4, v228
	v_mul_u32_u24_e32 v140, 0xf00, v140
	v_and_b32_e32 v141, 15, v228
	v_lshl_add_u32 v140, v141, 3, v140
	v_sub_u32_e32 v140, v196, v140
	s_nop 0
	v_readfirstlane_b32 s99, v140
	s_lshl_b32 s99, s99, 1
	s_add_i32 s99, s99, 0xf0000
	v_and_b32_e32 v140, 63, v228
	v_lshrrev_b32_e32 v141, 6, v228
	v_lshl_add_u32 v140, v141, 7, v140
	v_add_u32_e32 v141, 64, v140
	v_and_b32_e32 v142, 63, v228
	v_add_u32_e32 v142, 0x400, v142
	v_mul_u32_u24_e32 v132, 0xf10, v140
	v_mul_u32_u24_e32 v133, 0xf10, v141
	v_mul_u32_u24_e32 v134, 0xf10, v142
	v_lshrrev_b32_e32 v132, 16, v132
	v_lshrrev_b32_e32 v133, 16, v133
	v_lshrrev_b32_e32 v134, 16, v134
	v_mul_u32_u24_e32 v135, 17, v132
	v_sub_u32_e32 v140, v140, v135
	v_mul_u32_u24_e32 v135, 17, v133
	v_sub_u32_e32 v141, v141, v135
	v_mul_u32_u24_e32 v135, 17, v134
	v_sub_u32_e32 v142, v142, v135
	v_cmp_eq_u32_e32 vcc, 16, v140
	s_nop 1
	v_cndmask_b32_e64 v140, v140, 0, vcc
	v_cmp_eq_u32_e32 vcc, 16, v141
	s_nop 1
	v_cndmask_b32_e64 v141, v141, 0, vcc
	v_cmp_eq_u32_e32 vcc, 16, v142
	s_nop 1
	v_cndmask_b32_e64 v142, v142, 0, vcc
	v_mul_u32_u24_e32 v132, 0x1e00, v132
	v_mul_u32_u24_e32 v133, 0x1e00, v133
	v_mul_u32_u24_e32 v134, 0x1e00, v134
	v_lshl_add_u32 v132, v140, 4, v132
	v_lshl_add_u32 v133, v141, 4, v133
	v_lshl_add_u32 v134, v142, 4, v134
	v_lshrrev_b32_e32 v140, 3, v228
	v_lshlrev_b32_e32 v140, 14, v140
	v_and_b32_e32 v141, 7, v228
	v_lshl_add_u32 v140, v141, 3, v140
	v_sub_u32_e32 v140, v154, v140
	s_nop 0
	v_readfirstlane_b32 s101, v140
	s_lshl_b32 s101, s101, 1
	v_and_b32_e32 v140, 63, v228
	v_lshrrev_b32_e32 v141, 6, v228
	v_lshl_add_u32 v142, v141, 6, v140
	v_add_u32_e32 v142, 0x400, v142
	v_lshl_add_u32 v140, v141, 7, v140
	v_add_u32_e32 v141, 64, v140
	v_mul_u32_u24_e32 v135, 0x1c72, v140
	v_mul_u32_u24_e32 v136, 0x1c72, v141
	v_mul_u32_u24_e32 v137, 0x1c72, v142
	v_lshrrev_b32_e32 v135, 16, v135
	v_lshrrev_b32_e32 v136, 16, v136
	v_lshrrev_b32_e32 v137, 16, v137
	v_mul_u32_u24_e32 v143, 9, v135
	v_sub_u32_e32 v140, v140, v143
	v_mul_u32_u24_e32 v143, 9, v136
	v_sub_u32_e32 v141, v141, v143
	v_mul_u32_u24_e32 v143, 9, v137
	v_sub_u32_e32 v142, v142, v143
	v_cmp_ne_u32_e64 s[92:93], 8, v140
	v_cmp_ne_u32_e64 s[94:95], 8, v141
	v_cmp_ne_u32_e64 s[96:97], 8, v142
	v_cmp_eq_u32_e32 vcc, 8, v140
	s_nop 1
	v_cndmask_b32_e64 v140, v140, 0, vcc
	v_cmp_eq_u32_e32 vcc, 8, v141
	s_nop 1
	v_cndmask_b32_e64 v141, v141, 0, vcc
	v_cmp_eq_u32_e32 vcc, 8, v142
	s_nop 1
	v_cndmask_b32_e64 v142, v142, 0, vcc
	v_lshlrev_b32_e32 v135, 15, v135
	v_lshlrev_b32_e32 v136, 15, v136
	v_lshlrev_b32_e32 v137, 15, v137
	v_lshl_add_u32 v135, v140, 4, v135
	v_lshl_add_u32 v136, v141, 4, v136
	v_lshl_add_u32 v137, v142, 4, v137
	v_readfirstlane_b32 s100, v228
	s_lshr_b32 s100, s100, 8
	s_cmp_eq_u32 s100, 0
	s_cbranch_scc1 .Lattn_prio_skip
	s_setprio 1

; #define LAS __attribute__((address_space(3)))
; #define VLOAD(ks, DST) do { const LAS unsigned char* vp_ = Vb + (ks) * 32; \
;         _Pragma("unroll") for (int nb = 0; nb < NB; ++nb) DST[nb] = *(const LAS bf16x8*)(vp_ + nb * 32 * VTP); } while (0)
; #define SBAR_() __builtin_amdgcn_sched_barrier(0)
; template <int MODE, bool FROZEN = false>
; __device__ __forceinline__ bool attn_unit(LAS unsigned char* lds, const Params& p, int l, int ua, int ub) {
;     ...
;             for (int i = 0; i < NVC; ++i) { *(LAS u32x2*)(lds + vdst[i] + ((t + 1) & 1) * VBUF) = (u32x2){vr[i].x, vr[i].y}; *(LAS u32x2*)(lds + vdst[i] + ((t + 1) & 1) * VBUF + 16) = (u32x2){vr[i].z, vr[i].w}; }
;         }
;         {
;             const size_t advk = (size_t)min(t + 3, NT - 1) * 64 * NPROJ, advv = (size_t)min(t + 2, NT - 1) * 64;
; #pragma unroll
;             for (int i = 0; i < NKC; ++i) kr[i] = *(const u32x4*)(kvbase + advk + ksrc[i]);
; #pragma unroll
;             for (int i = 0; i < NVC; ++i) vr[i] = *(const u32x4*)(vtbase + advv + vsrc[i]);
;         }
;         f32x16 sA0 = sB0, sA1 = sB1;
;         const float c2 = cbB - m_run;
;         const LAS unsigned char* Vb = lds + OFF_V + (t & 1) * VBUF + vlane_off;
;         const LAS unsigned char* Kb = lds + OFF_K + ((t + 1) & 1) * KBUF + klane_off;
;     ...
;         bf16x8 kf0[4], kf1[4], va[NB], vb[NB], pf0, pf1; float ps0, ps1, ps2, ps3;
;         VLOAD(0, va);
;         EXPCVT(0, pf0, ps0);
;         SBAR_();
;         VLOAD(1, vb); PVMMA(va, pf0); EXPCVT(1, pf1, ps1); _Pragma("unroll") for (int g_ = 0; g_ < NB; ++g_) { __builtin_amdgcn_sched_group_barrier(0x008, 1, 0); __builtin_amdgcn_sched_group_barrier(0x100, 1, 0); __builtin_amdgcn_sched_group_barrier(0x400, 8 / NB, 0); __builtin_amdgcn_sched_group_barrier(0x002, 12 / NB, 0); } SBAR_();
;         VLOAD(2, va);
; #pragma unroll
;         for (int d0 = 0; d0 < 4; ++d0) { kf0[d0] = *(const LAS bf16x8*)(Kb + d0 * 32); kf1[d0] = *(const LAS bf16x8*)(Kb + 32 * KPB + d0 * 32); }
;         PVMMA(vb, pf1); EXPCVT(2, pf0, ps2); _Pragma("unroll") for (int g_ = 0; g_ < NB; ++g_) { __builtin_amdgcn_sched_group_barrier(0x008, 1, 0); __builtin_amdgcn_sched_group_barrier(0x100, 1, 0); __builtin_amdgcn_sched_group_barrier(0x400, 8 / NB, 0); __builtin_amdgcn_sched_group_barrier(0x002, 12 / NB, 0); } SBAR_();
.Lkdma_skip:
	v_add_u32_e32 v195, s15, v166
	v_cvt_pk_bf16_f32 v19, v109, v110
	s_waitcnt lgkmcnt(3)
	s_nop 0
	v_mfma_f32_32x32x16_bf16 v[36:51], v[112:115], v[16:19], v[36:51]
	ds_read_b128 v[20:23], v194 offset:34848
	ds_read_b128 v[218:221], v195 offset:32
	s_sub_i32 s10, 0xd000, s100
	s_mov_b64 exec, s[92:93]
	s_add_i32 m0, s10, s98
	s_nop 0
	global_load_lds_dwordx4 v135, s[0:1]
	s_mov_b64 exec, -1
	v_exp_f32_e32 v111, v24
	v_exp_f32_e32 v112, v25
	s_nop 0
	v_cvt_pk_bf16_f32 v24, v111, v112
	s_waitcnt lgkmcnt(4)
	v_mfma_f32_32x32x16_bf16 v[84:99], v[170:173], v[16:19], v[84:99]
	ds_read_b128 v[182:185], v194 offset:39456
	ds_read_b128 v[222:225], v195 offset:64
	s_mov_b64 exec, s[94:95]
	s_add_i32 m0, m0, 0x400
	s_nop 0
	global_load_lds_dwordx4 v136, s[0:1]
	s_mov_b64 exec, -1
	v_exp_f32_e32 v113, v26
	v_exp_f32_e32 v114, v27
	s_nop 0
	v_cvt_pk_bf16_f32 v25, v113, v114
	s_waitcnt lgkmcnt(5)
	v_mfma_f32_32x32x16_bf16 v[68:83], v[174:177], v[16:19], v[68:83]
	ds_read_b128 v[186:189], v194 offset:44064
	ds_read_b128 v[248:251], v195 offset:96
	s_cmp_gt_u32 s98, 0x800
	s_cbranch_scc1 .Lvdma_skip
	s_lshr_b32 s11, s98, 1
	s_add_i32 s11, s11, s10
	s_mov_b64 exec, s[96:97]
	s_add_i32 m0, s11, 0x4000
	s_nop 0
	global_load_lds_dwordx4 v137, s[0:1]
	s_mov_b64 exec, -1
